# speedup vs baseline: 1.0084x; 1.0005x over previous
; __device__ __forceinline__ float wave_sum(float v) {
; #pragma unroll
;     for (int o = 32; o >= 1; o >>= 1) v += __shfl_xor(v, o);
;     return v;
; }
; __device__ __forceinline__ void rowpass_init(const Params& p) {
;     ...
;         float4 v[4]; float ss = 0.f;
; #pragma unroll
;         for (int i = 0; i < 4; ++i) {
;             v[i] = *(const float4*)(src + lane * 4 + 256 * i);
;             ss += v[i].x * v[i].x + v[i].y * v[i].y + v[i].z * v[i].z + v[i].w * v[i].w;
;             if (pos < NMETA) *(float4*)(hp + lane * 4 + 256 * i) = v[i];
;         }
;         ss = wave_sum(ss);
;         float r = rsqrtf(ss * (1.0f / DM) + EPS);
; #pragma unroll
;         for (int i = 0; i < 4; ++i) {
;             float4 gg = *(const float4*)(g + lane * 4 + 256 * i);
;             uint2 o; o.x = pack2(v[i].x * r * gg.x, v[i].y * r * gg.y); o.y = pack2(v[i].z * r * gg.z, v[i].w * r * gg.w);
;             *(uint2*)(XU + (size_t)row * DM + lane * 4 + 256 * i) = o;
;         }
.LBB0_22:
	s_or_b64 exec, exec, s[0:1]
	global_load_dwordx4 v[38:41], v[22:23], off
	s_waitcnt vmcnt(4)
	v_pk_mul_f32 v[28:29], v[2:3], v[2:3]
	s_waitcnt vmcnt(3)
	v_pk_mul_f32 v[44:45], v[10:11], v[10:11]
	v_pk_mul_f32 v[42:43], v[4:5], v[4:5]
	v_pk_mul_f32 v[46:47], v[12:13], v[12:13]
	s_waitcnt vmcnt(2)
	v_pk_mul_f32 v[48:49], v[14:15], v[14:15]
	v_add_f32_e32 v18, v44, v45
	v_add_f32_e32 v21, v28, v29
	v_pk_mul_f32 v[50:51], v[16:17], v[16:17]
	s_waitcnt vmcnt(1)
	v_pk_mul_f32 v[52:53], v[6:7], v[6:7]
	v_add_f32_e32 v28, v48, v49
	v_add_f32_e32 v18, v18, v46
	v_add_f32_e32 v21, v21, v42
	v_pk_mul_f32 v[54:55], v[8:9], v[8:9]
	v_add_f32_e32 v29, v52, v53
	v_add_f32_e32 v28, v28, v50
	v_add_f32_e32 v18, v18, v47
	v_add_f32_e32 v21, v21, v43
	v_add_f32_e32 v29, v29, v54
	v_add_f32_e32 v28, v28, v51
	v_add_f32_e32 v18, v21, v18
	v_add_f32_e32 v29, v29, v55
	v_add_f32_e32 v18, v18, v28
	v_add_f32_e32 v18, v18, v29
	s_nop 1
	v_add_f32_dpp v18, v18, v18 row_ror:8 row_mask:0xf bank_mask:0xf
	s_nop 1
	v_add_f32_dpp v18, v18, v18 row_ror:4 row_mask:0xf bank_mask:0xf
	s_nop 1
	v_add_f32_dpp v18, v18, v18 row_ror:2 row_mask:0xf bank_mask:0xf
	s_nop 1
	v_add_f32_dpp v18, v18, v18 row_ror:1 row_mask:0xf bank_mask:0xf
	s_nop 1
	v_add_f32_dpp v18, v18, v18 row_bcast:15 row_mask:0xa bank_mask:0xf
	s_nop 1
	v_add_f32_dpp v18, v18, v18 row_bcast:31 row_mask:0xc bank_mask:0xf
	v_mov_b32_e32 v21, 0xfc
	ds_bpermute_b32 v21, v21, v18
	s_waitcnt lgkmcnt(0)
	v_mov_b32_e32 v18, v21
	v_fmamk_f32 v18, v18, 0x3a800000, v36
	v_mul_f32_e32 v21, 0x4b800000, v18
	v_cmp_gt_f32_e32 vcc, s17, v18
	s_nop 1
	v_cndmask_b32_e32 v18, v18, v21, vcc
	v_rsq_f32_e32 v18, v18
	v_ashrrev_i32_e32 v21, 31, v20
	v_lshlrev_b64 v[28:29], 11, v[20:21]
	v_lshl_add_u64 v[28:29], v[24:25], 0, v[28:29]
	v_mul_f32_e32 v21, 0x45800000, v18
	v_cndmask_b32_e32 v18, v18, v21, vcc
	v_pk_mul_f32 v[2:3], v[2:3], v[18:19] op_sel_hi:[1,0]
	v_pk_mul_f32 v[4:5], v[4:5], v[18:19] op_sel_hi:[1,0]
	v_pk_mul_f32 v[10:11], v[10:11], v[18:19] op_sel_hi:[1,0]
	v_pk_mul_f32 v[12:13], v[12:13], v[18:19] op_sel_hi:[1,0]
	v_add_u32_e32 v20, s14, v20
	v_pk_mul_f32 v[6:7], v[6:7], v[18:19] op_sel_hi:[1,0]
	v_pk_mul_f32 v[8:9], v[8:9], v[18:19] op_sel_hi:[1,0]
	v_cmp_lt_i32_e32 vcc, s18, v20
	s_waitcnt vmcnt(0)
	v_pk_mul_f32 v[2:3], v[38:39], v[2:3]
	v_pk_mul_f32 v[4:5], v[40:41], v[4:5]
	v_cvt_pk_bf16_f32 v2, v2, v3
	v_cvt_pk_bf16_f32 v3, v4, v5
	global_store_dwordx2 v[28:29], v[2:3], off
	global_load_dwordx4 v[2:5], v[22:23], off offset:1024
	s_or_b64 s[8:9], vcc, s[8:9]
	s_waitcnt vmcnt(0)
	v_pk_mul_f32 v[2:3], v[2:3], v[10:11]
	v_pk_mul_f32 v[4:5], v[4:5], v[12:13]
	v_cvt_pk_bf16_f32 v2, v2, v3
	v_cvt_pk_bf16_f32 v3, v4, v5
	global_store_dwordx2 v[28:29], v[2:3], off offset:512
	global_load_dwordx4 v[2:5], v[22:23], off offset:2048
	v_pk_mul_f32 v[10:11], v[14:15], v[18:19] op_sel_hi:[1,0]
	v_pk_mul_f32 v[12:13], v[16:17], v[18:19] op_sel_hi:[1,0]
	s_waitcnt vmcnt(0)
	v_pk_mul_f32 v[2:3], v[10:11], v[2:3]
	v_pk_mul_f32 v[4:5], v[12:13], v[4:5]
	v_cvt_pk_bf16_f32 v2, v2, v3
	v_cvt_pk_bf16_f32 v3, v4, v5
	global_store_dwordx2 v[28:29], v[2:3], off offset:1024
	global_load_dwordx4 v[2:5], v[22:23], off offset:3072
	s_waitcnt vmcnt(0)
	v_pk_mul_f32 v[2:3], v[6:7], v[2:3]
	v_pk_mul_f32 v[4:5], v[8:9], v[4:5]
	v_cvt_pk_bf16_f32 v2, v2, v3
	v_cvt_pk_bf16_f32 v3, v4, v5
	global_store_dwordx2 v[28:29], v[2:3], off offset:1536
	s_andn2_b64 exec, exec, s[8:9]
	s_cbranch_execz .LBB0_39

; __device__ __forceinline__ float bf2f(bf16_t h) { return __uint_as_float(((unsigned)h) << 16); }
; __device__ __forceinline__ bf16_t f2bf(float f) { return (bf16_t)(pack2(f, 0.0f) & 0xFFFFu); }
; __device__ __forceinline__ void rowpass_mla(const Params& p, int j) {
;     ...
;     for (int row = blockIdx.x * 8 + w; row < T; row += gridDim.x * 8) {
;         const bf16_t* cp = cin + (size_t)row * 768;
;         int pos = row % L;
;         float a[6]; float ss = 0.f;
; #pragma unroll
;         for (int i = 0; i < 6; ++i) { a[i] = bf2f(cp[lane + 64 * i]); ss += a[i] * a[i]; }
;         ss = wave_sum(ss);
;         float r = rsqrtf(ss * (1.0f / 384.0f) + EPS);
; #pragma unroll
;         for (int i = 0; i < 6; ++i) cqn[(size_t)row * 384 + lane + 64 * i] = f2bf(a[i] * r * gq[lane + 64 * i]);
;         float c[4]; float s2 = 0.f;
; #pragma unroll
;         for (int i = 0; i < 4; ++i) { c[i] = bf2f(cp[384 + lane + 64 * i]); s2 += c[i] * c[i]; }
;         s2 = wave_sum(s2);
;         float r2 = rsqrtf(s2 * (1.0f / 256.0f) + EPS);
; #pragma unroll
;         for (int i = 0; i < 4; ++i) ckvn[(size_t)row * 256 + lane + 64 * i] = f2bf(c[i] * r2 * gkv[lane + 64 * i]);
;         float x = bf2f(cp[640 + lane]);
;         float xo = __shfl_xor(x, 32);
;         int fi = lane & 31;
;         float cs = ct[pos * 32 + fi], sn = st[pos * 32 + fi];
;         float o = lane < 32 ? (x * cs - xo * sn) : (x * cs + xo * sn);
;         krope[(size_t)row * 64 + lane] = f2bf(o);
;     }
.LBB0_682:
	v_add_u32_e32 v72, s66, v2
	v_min_i32_e32 v72, s9, v72
	v_mad_i64_i32 v[66:67], s[0:1], v72, s40, v[10:11]
	global_load_ushort v53, v[66:67], off
	global_load_ushort v54, v[66:67], off offset:128
	global_load_ushort v55, v[66:67], off offset:256
	global_load_ushort v56, v[66:67], off offset:384
	global_load_ushort v57, v[66:67], off offset:512
	global_load_ushort v58, v[66:67], off offset:640
	global_load_ushort v59, v[66:67], off offset:768
	global_load_ushort v60, v[66:67], off offset:896
	global_load_ushort v61, v[66:67], off offset:1024
	global_load_ushort v62, v[66:67], off offset:1152
	global_load_ushort v63, v[66:67], off offset:1280
	v_mul_hi_i32 v68, v72, s7
	v_lshrrev_b32_e32 v69, 31, v68
	v_ashrrev_i32_e32 v68, 11, v68
	v_add_u32_e32 v68, v68, v69
	v_mul_i32_i24_e32 v68, 0x1010, v68
	v_sub_u32_e32 v68, v72, v68
	v_lshl_or_b32 v68, v68, 5, v31
	v_ashrrev_i32_e32 v69, 31, v68
	v_lshlrev_b64 v[68:69], 2, v[68:69]
	v_lshl_add_u64 v[70:71], s[10:11], 0, v[68:69]
	global_load_dword v64, v[70:71], off
	v_lshl_add_u64 v[70:71], s[12:13], 0, v[68:69]
	global_load_dword v65, v[70:71], off
	v_ashrrev_i32_e32 v3, 31, v2
	v_lshlrev_b32_e32 v0, 16, v40
	v_lshlrev_b32_e32 v38, 16, v41
	v_mul_f32_e32 v36, v38, v38
	v_fmac_f32_e32 v36, v0, v0
	v_lshlrev_b32_e32 v32, 16, v42
	v_lshlrev_b32_e32 v33, 16, v43
	v_pk_mul_f32 v[34:35], v[32:33], v[32:33]
	s_nop 0
	v_add_f32_e32 v34, v36, v34
	v_add_f32_e32 v39, v34, v35
	v_lshlrev_b32_e32 v34, 16, v44
	v_lshlrev_b32_e32 v35, 16, v45
	v_pk_mul_f32 v[36:37], v[34:35], v[34:35]
	s_nop 0
	v_add_f32_e32 v36, v39, v36
	v_add_f32_e32 v36, v36, v37
	s_nop 1
	v_add_f32_dpp v36, v36, v36 row_ror:8 row_mask:0xf bank_mask:0xf
	s_nop 1
	v_add_f32_dpp v36, v36, v36 row_ror:4 row_mask:0xf bank_mask:0xf
	s_nop 1
	v_add_f32_dpp v36, v36, v36 row_ror:2 row_mask:0xf bank_mask:0xf
	s_nop 1
	v_add_f32_dpp v36, v36, v36 row_ror:1 row_mask:0xf bank_mask:0xf
	s_nop 1
	v_add_f32_dpp v36, v36, v36 row_bcast:15 row_mask:0xa bank_mask:0xf
	s_nop 1
	v_add_f32_dpp v36, v36, v36 row_bcast:31 row_mask:0xc bank_mask:0xf
	v_mov_b32_e32 v37, 0xfc
	ds_bpermute_b32 v37, v37, v36
	s_waitcnt lgkmcnt(0)
	v_mov_b32_e32 v36, v37
	v_fmamk_f32 v36, v36, 0x3b2aaaab, v174
	v_cmp_gt_f32_e64 s[0:1], s8, v36
	v_mul_f32_e32 v37, 0x4b800000, v36
	s_nop 0
	v_cndmask_b32_e64 v36, v36, v37, s[0:1]
	v_rsq_f32_e32 v36, v36
	s_nop 0
	v_mul_f32_e32 v37, 0x45800000, v36
	v_cndmask_b32_e64 v39, v36, v37, s[0:1]
	v_mul_f32_e32 v0, v39, v0
	v_mad_i64_i32 v[36:37], s[0:1], v2, s6, v[4:5]
	v_mul_f32_e32 v0, v17, v0
	s_nop 0
	v_cvt_pk_bf16_f32 v0, v0, s0
	global_store_short v[36:37], v0, off
	v_mul_f32_e32 v0, v39, v38
	v_mul_f32_e32 v0, v18, v0
	v_cvt_pk_bf16_f32 v0, v0, s0
	global_store_short v[36:37], v0, off offset:128
	v_mul_f32_e32 v0, v39, v32
	v_mul_f32_e32 v0, v19, v0
	v_cvt_pk_bf16_f32 v0, v0, s0
	global_store_short v[36:37], v0, off offset:256
	v_mul_f32_e32 v0, v39, v33
	v_mul_f32_e32 v0, v20, v0
	v_cvt_pk_bf16_f32 v0, v0, s0
	global_store_short v[36:37], v0, off offset:384
	v_mul_f32_e32 v0, v39, v34
	v_mul_f32_e32 v0, v15, v0
	v_cvt_pk_bf16_f32 v0, v0, s0
	global_store_short v[36:37], v0, off offset:512
	v_mul_f32_e32 v0, v39, v35
	v_mul_f32_e32 v0, v16, v0
	v_cvt_pk_bf16_f32 v0, v0, s0
	global_store_short v[36:37], v0, off offset:640
	v_lshlrev_b32_e32 v33, 16, v47
	v_lshlrev_b32_e32 v32, 16, v46
	v_pk_mul_f32 v[34:35], v[32:33], v[32:33]
	v_lshlrev_b32_e32 v37, 16, v49
	v_lshlrev_b32_e32 v36, 16, v48
	v_pk_mul_f32 v[38:39], v[36:37], v[36:37]
	v_add_f32_e32 v0, v34, v35
	v_add_f32_e32 v0, v0, v38
	v_add_f32_e32 v0, v0, v39
	s_nop 1
	v_add_f32_dpp v0, v0, v0 row_ror:8 row_mask:0xf bank_mask:0xf
	s_nop 1
	v_add_f32_dpp v0, v0, v0 row_ror:4 row_mask:0xf bank_mask:0xf
	s_nop 1
	v_add_f32_dpp v0, v0, v0 row_ror:2 row_mask:0xf bank_mask:0xf
	s_nop 1
	v_add_f32_dpp v0, v0, v0 row_ror:1 row_mask:0xf bank_mask:0xf
	s_nop 1
	v_add_f32_dpp v0, v0, v0 row_bcast:15 row_mask:0xa bank_mask:0xf
	s_nop 1
	v_add_f32_dpp v0, v0, v0 row_bcast:31 row_mask:0xc bank_mask:0xf
	v_mov_b32_e32 v34, 0xfc
	ds_bpermute_b32 v34, v34, v0
	s_waitcnt lgkmcnt(0)
	v_mov_b32_e32 v0, v34
	v_fmamk_f32 v0, v0, 0x3b800000, v174
	v_cmp_gt_f32_e64 s[0:1], s8, v0
	v_mul_f32_e32 v34, 0x4b800000, v0
	s_nop 0
	v_cndmask_b32_e64 v0, v0, v34, s[0:1]
	v_rsq_f32_e32 v0, v0
	s_nop 0
	v_mul_f32_e32 v34, 0x45800000, v0
	v_cndmask_b32_e64 v0, v0, v34, s[0:1]
	v_mul_f32_e32 v32, v0, v32
	v_lshlrev_b64 v[34:35], 9, v[2:3]
	v_mul_f32_e32 v32, v21, v32
	v_lshl_add_u64 v[34:35], v[6:7], 0, v[34:35]
	v_cvt_pk_bf16_f32 v32, v32, s0
	global_store_short v[34:35], v32, off
	v_mul_f32_e32 v32, v0, v33
	v_mul_f32_e32 v32, v22, v32
	v_cvt_pk_bf16_f32 v32, v32, s0
	global_store_short v[34:35], v32, off offset:128
	v_mul_f32_e32 v32, v0, v36
	v_mul_f32_e32 v32, v23, v32
	v_cvt_pk_bf16_f32 v32, v32, s0
	global_store_short v[34:35], v32, off offset:256
	v_mul_f32_e32 v0, v0, v37
	v_mul_f32_e32 v0, v24, v0
	v_cvt_pk_bf16_f32 v0, v0, s0
	global_store_short v[34:35], v0, off offset:384
	v_lshlrev_b32_e32 v34, 16, v50
	s_nop 0
	ds_bpermute_b32 v35, v25, v34
	s_waitcnt lgkmcnt(0)
	v_mul_f32_e32 v12, v52, v35
	v_cndmask_b32_e64 v12, v12, -v12, vcc
	v_fmac_f32_e32 v12, v51, v34
	v_cvt_pk_bf16_f32 v0, v12, s0
	v_lshlrev_b64 v[12:13], 7, v[2:3]
	v_lshl_add_u64 v[12:13], v[8:9], 0, v[12:13]
	global_store_short v[12:13], v0, off
	s_waitcnt vmcnt(11)
	v_mov_b32_e32 v40, v53
	v_mov_b32_e32 v41, v54
	v_mov_b32_e32 v42, v55
	v_mov_b32_e32 v43, v56
	v_mov_b32_e32 v44, v57
	v_mov_b32_e32 v45, v58
	v_mov_b32_e32 v46, v59
	v_mov_b32_e32 v47, v60
	v_mov_b32_e32 v48, v61
	v_mov_b32_e32 v49, v62
	v_mov_b32_e32 v50, v63
	v_mov_b32_e32 v51, v64
	v_mov_b32_e32 v52, v65
	v_add_u32_e32 v2, s66, v2
	v_cmp_lt_i32_e64 s[0:1], s9, v2
	s_or_b64 s[4:5], s[0:1], s[4:5]
	s_andn2_b64 exec, exec, s[4:5]
	s_cbranch_execnz .LBB0_682

; __device__ __forceinline__ float bf2f(bf16_t h) { return __uint_as_float(((unsigned)h) << 16); }
; __device__ __forceinline__ void rowpass_resid(const Params& p, const float* __restrict__ ga, const float* __restrict__ gb, bool write_xn, bool from_x = false) {
;     ...
;     for (int row = blockIdx.x * 8 + w; row < T; row += gridDim.x * 8) {
;         float* hp = hrow(p, row);
;         const float* hsrc = hp;
;         if (from_x) { const int b_ = row / L, pos_ = row - b_ * L; if (pos_ >= NMETA) hsrc = p.in[0] + ((size_t)b_ * SEQ + pos_ - NMETA) * DM; }
;         bf16_t* xp = XU + (size_t)row * DM;
;         float u[16]; float ss = 0.f;
; #pragma unroll
;         for (int i = 0; i < 4; ++i) {
;             uint2 q = *(const uint2*)(xp + lane * 4 + 256 * i);
;             u[4 * i + 0] = bf2f((bf16_t)(q.x & 0xFFFF)); u[4 * i + 1] = bf2f((bf16_t)(q.x >> 16));
;             u[4 * i + 2] = bf2f((bf16_t)(q.y & 0xFFFF)); u[4 * i + 3] = bf2f((bf16_t)(q.y >> 16));
; #pragma unroll
;             for (int j = 0; j < 4; ++j) ss += u[4 * i + j] * u[4 * i + j];
;         }
;         ss = wave_sum(ss);
;         float r = rsqrtf(ss * (1.0f / DM) + EPS);
;         float hv[16]; float s2 = 0.f;
; #pragma unroll
;         for (int i = 0; i < 4; ++i) {
;             float4 h4 = *(const float4*)(hsrc + lane * 4 + 256 * i);
;             float4 g4 = *(const float4*)(ga + lane * 4 + 256 * i);
;             hv[4 * i + 0] = h4.x + u[4 * i + 0] * r * g4.x;
;             hv[4 * i + 1] = h4.y + u[4 * i + 1] * r * g4.y;
;             hv[4 * i + 2] = h4.z + u[4 * i + 2] * r * g4.z;
;             hv[4 * i + 3] = h4.w + u[4 * i + 3] * r * g4.w;
;             *(float4*)(hp + lane * 4 + 256 * i) = make_float4(hv[4 * i], hv[4 * i + 1], hv[4 * i + 2], hv[4 * i + 3]);
; #pragma unroll
;             for (int j = 0; j < 4; ++j) s2 += hv[4 * i + j] * hv[4 * i + j];
;         }
.LBB0_977:
	s_or_b64 exec, exec, s[8:9]
	v_readlane_b32 s68, v252, 4
	v_readlane_b32 s69, v252, 5
	v_lshlrev_b64 v[44:45], 12, v[0:1]
	s_mov_b32 s8, 0xffff0000
	v_lshl_add_u64 v[40:41], s[68:69], 0, v[40:41]
	v_lshlrev_b64 v[42:43], 12, v[42:43]
	v_cmp_lt_i32_e32 vcc, 15, v0
	v_lshl_add_u64 v[40:41], v[40:41], 0, v[44:45]
	s_mov_b32 s9, -1
	v_lshl_add_u64 v[42:43], v[46:47], 0, v[42:43]
	s_and_b64 vcc, s[2:3], vcc
	v_lshl_add_u64 v[40:41], v[40:41], 0, s[8:9]
	v_ashrrev_i32_e32 v35, 31, v34
	v_cndmask_b32_e32 v45, v43, v41, vcc
	v_cndmask_b32_e32 v44, v42, v40, vcc
	v_lshlrev_b64 v[40:41], 11, v[34:35]
	v_lshl_add_u64 v[40:41], v[36:37], 0, v[40:41]
	global_load_dwordx2 v[88:89], v[40:41], off
	global_load_dwordx2 v[90:91], v[40:41], off offset:512
	global_load_dwordx2 v[92:93], v[40:41], off offset:1024
	global_load_dwordx2 v[94:95], v[40:41], off offset:1536
	v_mov_b32_e32 v39, v1
	v_lshl_add_u64 v[70:71], v[44:45], 0, v[38:39]
	v_lshl_add_u64 v[72:73], v[42:43], 0, v[38:39]
	global_load_dwordx4 v[42:45], v[70:71], off
	global_load_dwordx4 v[96:99], v[70:71], off offset:1024
	global_load_dwordx4 v[100:103], v[70:71], off offset:2048
	global_load_dwordx4 v[104:107], v[70:71], off offset:3072
	s_mov_b32 s8, 0x800000
	v_add_u32_e32 v34, s66, v34
	s_waitcnt vmcnt(4)
	v_lshlrev_b32_e32 v54, 16, v88
	v_and_b32_e32 v55, 0xffff0000, v88
	v_lshlrev_b32_e32 v46, 16, v89
	v_and_b32_e32 v47, 0xffff0000, v89
	v_lshlrev_b32_e32 v58, 16, v90
	v_and_b32_e32 v59, 0xffff0000, v90
	v_lshlrev_b32_e32 v60, 16, v91
	v_and_b32_e32 v61, 0xffff0000, v91
	v_lshlrev_b32_e32 v62, 16, v92
	v_and_b32_e32 v63, 0xffff0000, v92
	v_lshlrev_b32_e32 v64, 16, v93
	v_and_b32_e32 v65, 0xffff0000, v93
	v_lshlrev_b32_e32 v66, 16, v94
	v_and_b32_e32 v67, 0xffff0000, v94
	v_lshlrev_b32_e32 v68, 16, v95
	v_and_b32_e32 v69, 0xffff0000, v95
	v_pk_mul_f32 v[74:75], v[46:47], v[46:47]
	v_pk_mul_f32 v[76:77], v[58:59], v[58:59]
	v_pk_mul_f32 v[78:79], v[60:61], v[60:61]
	v_pk_mul_f32 v[80:81], v[62:63], v[62:63]
	v_pk_mul_f32 v[82:83], v[64:65], v[64:65]
	v_pk_mul_f32 v[56:57], v[54:55], v[54:55]
	v_pk_mul_f32 v[84:85], v[66:67], v[66:67]
	v_add_f32_e32 v0, v56, v57
	v_add_f32_e32 v0, v0, v74
	v_add_f32_e32 v0, v75, v0
	v_add_f32_e32 v0, v76, v0
	v_add_f32_e32 v0, v77, v0
	v_add_f32_e32 v0, v78, v0
	v_add_f32_e32 v0, v79, v0
	v_add_f32_e32 v0, v80, v0
	v_add_f32_e32 v0, v81, v0
	v_add_f32_e32 v0, v82, v0
	v_add_f32_e32 v0, v83, v0
	v_add_f32_e32 v0, v84, v0
	v_pk_mul_f32 v[86:87], v[68:69], v[68:69]
	v_add_f32_e32 v0, v85, v0
	v_add_f32_e32 v0, v86, v0
	v_add_f32_e32 v0, v87, v0
	s_nop 1
	v_add_f32_dpp v0, v0, v0 row_ror:8 row_mask:0xf bank_mask:0xf
	s_nop 1
	v_add_f32_dpp v0, v0, v0 row_ror:4 row_mask:0xf bank_mask:0xf
	s_nop 1
	v_add_f32_dpp v0, v0, v0 row_ror:2 row_mask:0xf bank_mask:0xf
	s_nop 1
	v_add_f32_dpp v0, v0, v0 row_ror:1 row_mask:0xf bank_mask:0xf
	s_nop 1
	v_add_f32_dpp v0, v0, v0 row_bcast:15 row_mask:0xa bank_mask:0xf
	s_nop 1
	v_add_f32_dpp v0, v0, v0 row_bcast:31 row_mask:0xc bank_mask:0xf
	v_mov_b32_e32 v35, 0xfc
	ds_bpermute_b32 v35, v35, v0
	s_waitcnt lgkmcnt(0)
	v_mov_b32_e32 v0, v35
	v_fmamk_f32 v0, v0, 0x3a800000, v174
	v_cmp_gt_f32_e32 vcc, s8, v0
	v_mul_f32_e32 v35, 0x4b800000, v0
	s_nop 0
	v_cndmask_b32_e32 v0, v0, v35, vcc
	v_rsq_f32_e32 v0, v0
	s_nop 0
	v_mul_f32_e32 v35, 0x45800000, v0
	v_cndmask_b32_e32 v0, v0, v35, vcc
	v_pk_mul_f32 v[54:55], v[0:1], v[54:55] op_sel_hi:[0,1]
	v_pk_mul_f32 v[46:47], v[0:1], v[46:47] op_sel_hi:[0,1]
	s_waitcnt vmcnt(3)
	v_pk_fma_f32 v[42:43], v[10:11], v[54:55], v[42:43]
	v_pk_fma_f32 v[44:45], v[12:13], v[46:47], v[44:45]
	global_store_dwordx4 v[72:73], v[42:45], off
	v_pk_mul_f32 v[46:47], v[0:1], v[58:59] op_sel_hi:[0,1]
	s_waitcnt vmcnt(3)
; __device__ __forceinline__ void rowpass_resid(const Params& p, const float* __restrict__ ga, const float* __restrict__ gb, bool write_xn, bool from_x = false) {
;     ...
;             for (int j = 0; j < 4; ++j) s2 += hv[4 * i + j] * hv[4 * i + j];
;         }
;         if (write_xn) {
;             s2 = wave_sum(s2);
;             float r2 = rsqrtf(s2 * (1.0f / DM) + EPS);
; #pragma unroll
;             for (int i = 0; i < 4; ++i) {
;                 float4 g4 = *(const float4*)(gb + lane * 4 + 256 * i);
;                 uint2 o; o.x = pack2(hv[4 * i] * r2 * g4.x, hv[4 * i + 1] * r2 * g4.y);
;                 o.y = pack2(hv[4 * i + 2] * r2 * g4.z, hv[4 * i + 3] * r2 * g4.w);
;                 *(uint2*)(xp + lane * 4 + 256 * i) = o;
;             }
;         }
	v_pk_fma_f32 v[96:97], v[2:3], v[46:47], v[96:97]
	v_pk_mul_f32 v[46:47], v[0:1], v[60:61] op_sel_hi:[0,1]
	v_pk_fma_f32 v[98:99], v[4:5], v[46:47], v[98:99]
	global_store_dwordx4 v[72:73], v[96:99], off offset:1024
	v_pk_mul_f32 v[46:47], v[0:1], v[62:63] op_sel_hi:[0,1]
	s_waitcnt vmcnt(3)
	v_pk_fma_f32 v[100:101], v[6:7], v[46:47], v[100:101]
	v_pk_mul_f32 v[46:47], v[0:1], v[64:65] op_sel_hi:[0,1]
	v_pk_fma_f32 v[102:103], v[8:9], v[46:47], v[102:103]
	global_store_dwordx4 v[72:73], v[100:103], off offset:2048
	v_pk_mul_f32 v[46:47], v[0:1], v[66:67] op_sel_hi:[0,1]
	v_pk_mul_f32 v[66:67], v[44:45], v[44:45]
	v_pk_mul_f32 v[70:71], v[98:99], v[98:99]
	v_pk_mul_f32 v[74:75], v[102:103], v[102:103]
	s_waitcnt vmcnt(3)
	v_pk_fma_f32 v[104:105], v[18:19], v[46:47], v[104:105]
	v_pk_mul_f32 v[46:47], v[0:1], v[68:69] op_sel_hi:[0,1]
	v_pk_fma_f32 v[106:107], v[20:21], v[46:47], v[106:107]
	v_pk_mul_f32 v[46:47], v[42:43], v[42:43]
	v_pk_mul_f32 v[68:69], v[96:97], v[96:97]
	v_add_f32_e32 v0, v46, v47
	v_add_f32_e32 v0, v66, v0
	v_add_f32_e32 v0, v67, v0
	v_add_f32_e32 v0, v68, v0
	v_add_f32_e32 v0, v69, v0
	v_add_f32_e32 v0, v70, v0
	global_store_dwordx4 v[72:73], v[104:107], off offset:3072
	v_pk_mul_f32 v[72:73], v[100:101], v[100:101]
	v_add_f32_e32 v0, v71, v0
	v_add_f32_e32 v0, v72, v0
	v_add_f32_e32 v0, v73, v0
	v_add_f32_e32 v0, v74, v0
	v_pk_mul_f32 v[76:77], v[104:105], v[104:105]
	v_add_f32_e32 v0, v75, v0
	v_add_f32_e32 v0, v76, v0
	v_pk_mul_f32 v[78:79], v[106:107], v[106:107]
	v_add_f32_e32 v0, v77, v0
	v_add_f32_e32 v0, v78, v0
	v_add_f32_e32 v0, v79, v0
	s_nop 1
	v_add_f32_dpp v0, v0, v0 row_ror:8 row_mask:0xf bank_mask:0xf
	s_nop 1
	v_add_f32_dpp v0, v0, v0 row_ror:4 row_mask:0xf bank_mask:0xf
	s_nop 1
	v_add_f32_dpp v0, v0, v0 row_ror:2 row_mask:0xf bank_mask:0xf
	s_nop 1
	v_add_f32_dpp v0, v0, v0 row_ror:1 row_mask:0xf bank_mask:0xf
	s_nop 1
	v_add_f32_dpp v0, v0, v0 row_bcast:15 row_mask:0xa bank_mask:0xf
	s_nop 1
	v_add_f32_dpp v0, v0, v0 row_bcast:31 row_mask:0xc bank_mask:0xf
	v_mov_b32_e32 v35, 0xfc
	ds_bpermute_b32 v35, v35, v0
	s_waitcnt lgkmcnt(0)
	v_mov_b32_e32 v0, v35
	v_fmamk_f32 v0, v0, 0x3a800000, v174
	v_cmp_gt_f32_e32 vcc, s8, v0
	v_mul_f32_e32 v35, 0x4b800000, v0
	s_movk_i32 s8, 0x403f
	v_cndmask_b32_e32 v0, v0, v35, vcc
	v_rsq_f32_e32 v0, v0
	s_nop 0
	v_mul_f32_e32 v35, 0x45800000, v0
	v_cndmask_b32_e32 v0, v0, v35, vcc
	v_pk_mul_f32 v[42:43], v[42:43], v[0:1] op_sel_hi:[1,0]
	v_pk_mul_f32 v[44:45], v[44:45], v[0:1] op_sel_hi:[1,0]
	v_pk_mul_f32 v[42:43], v[14:15], v[42:43]
	v_pk_mul_f32 v[44:45], v[16:17], v[44:45]
	v_cvt_pk_bf16_f32 v42, v42, v43
	v_cvt_pk_bf16_f32 v43, v44, v45
	global_store_dwordx2 v[40:41], v[42:43], off
	v_pk_mul_f32 v[42:43], v[96:97], v[0:1] op_sel_hi:[1,0]
	v_pk_mul_f32 v[44:45], v[98:99], v[0:1] op_sel_hi:[1,0]
	v_pk_mul_f32 v[42:43], v[22:23], v[42:43]
	v_pk_mul_f32 v[44:45], v[24:25], v[44:45]
	v_cvt_pk_bf16_f32 v42, v42, v43
	v_cvt_pk_bf16_f32 v43, v44, v45
	global_store_dwordx2 v[40:41], v[42:43], off offset:512
	v_pk_mul_f32 v[42:43], v[100:101], v[0:1] op_sel_hi:[1,0]
	v_pk_mul_f32 v[44:45], v[102:103], v[0:1] op_sel_hi:[1,0]
	v_pk_mul_f32 v[42:43], v[42:43], v[26:27]
	v_pk_mul_f32 v[44:45], v[44:45], v[28:29]
	v_cvt_pk_bf16_f32 v42, v42, v43
	v_cvt_pk_bf16_f32 v43, v44, v45
	global_store_dwordx2 v[40:41], v[42:43], off offset:1024
	v_pk_mul_f32 v[42:43], v[104:105], v[0:1] op_sel_hi:[1,0]
	v_pk_mul_f32 v[44:45], v[106:107], v[0:1] op_sel_hi:[1,0]
	v_pk_mul_f32 v[42:43], v[42:43], v[30:31]
	v_pk_mul_f32 v[44:45], v[44:45], v[32:33]
	v_cmp_lt_i32_e32 vcc, s8, v34
	v_cvt_pk_bf16_f32 v42, v42, v43
	v_cvt_pk_bf16_f32 v43, v44, v45
	s_or_b64 s[4:5], vcc, s[4:5]
	global_store_dwordx2 v[40:41], v[42:43], off offset:1536
	s_andn2_b64 exec, exec, s[4:5]
	s_cbranch_execz .LBB0_982

; __device__ __forceinline__ float bf2f(bf16_t h) { return __uint_as_float(((unsigned)h) << 16); }
; __device__ __forceinline__ void rowpass_resid(const Params& p, const float* __restrict__ ga, const float* __restrict__ gb, bool write_xn, bool from_x = false) {
;     ...
;         float* hp = hrow(p, row);
;         const float* hsrc = hp;
;         if (from_x) { const int b_ = row / L, pos_ = row - b_ * L; if (pos_ >= NMETA) hsrc = p.in[0] + ((size_t)b_ * SEQ + pos_ - NMETA) * DM; }
;         bf16_t* xp = XU + (size_t)row * DM;
;         float u[16]; float ss = 0.f;
; #pragma unroll
;         for (int i = 0; i < 4; ++i) {
;             uint2 q = *(const uint2*)(xp + lane * 4 + 256 * i);
;             u[4 * i + 0] = bf2f((bf16_t)(q.x & 0xFFFF)); u[4 * i + 1] = bf2f((bf16_t)(q.x >> 16));
;             u[4 * i + 2] = bf2f((bf16_t)(q.y & 0xFFFF)); u[4 * i + 3] = bf2f((bf16_t)(q.y >> 16));
; #pragma unroll
;             for (int j = 0; j < 4; ++j) ss += u[4 * i + j] * u[4 * i + j];
;         }
;         ss = wave_sum(ss);
;         float r = rsqrtf(ss * (1.0f / DM) + EPS);
;         float hv[16]; float s2 = 0.f;
; #pragma unroll
;         for (int i = 0; i < 4; ++i) {
;             float4 h4 = *(const float4*)(hsrc + lane * 4 + 256 * i);
;             float4 g4 = *(const float4*)(ga + lane * 4 + 256 * i);
;             hv[4 * i + 0] = h4.x + u[4 * i + 0] * r * g4.x;
;             hv[4 * i + 1] = h4.y + u[4 * i + 1] * r * g4.y;
;             hv[4 * i + 2] = h4.z + u[4 * i + 2] * r * g4.z;
;             hv[4 * i + 3] = h4.w + u[4 * i + 3] * r * g4.w;
;             *(float4*)(hp + lane * 4 + 256 * i) = make_float4(hv[4 * i], hv[4 * i + 1], hv[4 * i + 2], hv[4 * i + 3]);
; #pragma unroll
;             for (int j = 0; j < 4; ++j) s2 += hv[4 * i + j] * hv[4 * i + j];
;         }
.LBB0_1215:
	s_or_b64 exec, exec, s[0:1]
	v_ashrrev_i32_e32 v35, 31, v34
	v_lshlrev_b64 v[22:23], 11, v[34:35]
	v_lshl_add_u64 v[40:41], v[38:39], 0, v[22:23]
	global_load_dwordx2 v[26:27], v[40:41], off
	global_load_dwordx2 v[28:29], v[40:41], off offset:512
	global_load_dwordx2 v[30:31], v[40:41], off offset:1024
	global_load_dwordx2 v[32:33], v[40:41], off offset:1536
	v_lshlrev_b64 v[18:19], 12, v[18:19]
	v_lshl_add_u64 v[18:19], v[20:21], 0, v[18:19]
	v_lshl_add_u64 v[58:59], v[18:19], 0, v[0:1]
	global_load_dwordx4 v[18:21], v[58:59], off
	global_load_dwordx4 v[22:25], v[58:59], off offset:1024
	global_load_dwordx4 v[50:53], v[58:59], off offset:2048
	global_load_dwordx4 v[54:57], v[58:59], off offset:3072
	s_mov_b32 s0, 0x800000
	s_and_b64 vcc, exec, s[4:5]
	s_waitcnt vmcnt(7)
	v_lshlrev_b32_e32 v60, 16, v26
	v_and_b32_e32 v61, 0xffff0000, v26
	v_lshlrev_b32_e32 v26, 16, v27
	v_and_b32_e32 v27, 0xffff0000, v27
	v_pk_mul_f32 v[70:71], v[60:61], v[60:61]
	v_pk_mul_f32 v[68:69], v[26:27], v[26:27]
	v_add_f32_e32 v35, v70, v71
	s_waitcnt vmcnt(6)
	v_lshlrev_b32_e32 v62, 16, v28
	v_and_b32_e32 v63, 0xffff0000, v28
	v_add_f32_e32 v35, v35, v68
	v_pk_mul_f32 v[74:75], v[62:63], v[62:63]
	v_add_f32_e32 v35, v69, v35
	v_lshlrev_b32_e32 v28, 16, v29
	v_and_b32_e32 v29, 0xffff0000, v29
	v_add_f32_e32 v35, v74, v35
	v_pk_mul_f32 v[72:73], v[28:29], v[28:29]
	v_add_f32_e32 v35, v75, v35
	s_waitcnt vmcnt(5)
	v_lshlrev_b32_e32 v64, 16, v30
	v_and_b32_e32 v65, 0xffff0000, v30
	v_add_f32_e32 v35, v72, v35
	v_pk_mul_f32 v[78:79], v[64:65], v[64:65]
	v_add_f32_e32 v35, v73, v35
	v_lshlrev_b32_e32 v30, 16, v31
	v_and_b32_e32 v31, 0xffff0000, v31
	v_add_f32_e32 v35, v78, v35
	v_pk_mul_f32 v[76:77], v[30:31], v[30:31]
	v_add_f32_e32 v35, v79, v35
	s_waitcnt vmcnt(4)
	v_lshlrev_b32_e32 v66, 16, v32
	v_and_b32_e32 v67, 0xffff0000, v32
	v_add_f32_e32 v35, v76, v35
	v_pk_mul_f32 v[82:83], v[66:67], v[66:67]
	v_add_f32_e32 v35, v77, v35
	v_lshlrev_b32_e32 v32, 16, v33
	v_and_b32_e32 v33, 0xffff0000, v33
	v_add_f32_e32 v35, v82, v35
	v_pk_mul_f32 v[80:81], v[32:33], v[32:33]
	v_add_f32_e32 v35, v83, v35
	v_add_f32_e32 v35, v80, v35
	v_add_f32_e32 v35, v81, v35
	s_nop 1
	v_add_f32_dpp v35, v35, v35 row_ror:8 row_mask:0xf bank_mask:0xf
	s_nop 1
	v_add_f32_dpp v35, v35, v35 row_ror:4 row_mask:0xf bank_mask:0xf
	s_nop 1
	v_add_f32_dpp v35, v35, v35 row_ror:2 row_mask:0xf bank_mask:0xf
	s_nop 1
	v_add_f32_dpp v35, v35, v35 row_ror:1 row_mask:0xf bank_mask:0xf
	s_nop 1
	v_add_f32_dpp v35, v35, v35 row_bcast:15 row_mask:0xa bank_mask:0xf
	s_nop 1
	v_add_f32_dpp v35, v35, v35 row_bcast:31 row_mask:0xc bank_mask:0xf
	v_mov_b32_e32 v42, 0xfc
	ds_bpermute_b32 v42, v42, v35
	s_waitcnt lgkmcnt(0)
	v_mov_b32_e32 v35, v42
	v_fmamk_f32 v35, v35, 0x3a800000, v174
	v_mul_f32_e32 v42, 0x4b800000, v35
	v_cmp_gt_f32_e64 s[0:1], s0, v35
	s_nop 1
	v_cndmask_b32_e64 v35, v35, v42, s[0:1]
	v_rsq_f32_e32 v35, v35
	s_nop 0
	v_mul_f32_e32 v42, 0x45800000, v35
	v_cndmask_b32_e64 v42, v35, v42, s[0:1]
	v_pk_mul_f32 v[60:61], v[42:43], v[60:61] op_sel_hi:[0,1]
	v_pk_mul_f32 v[26:27], v[42:43], v[26:27] op_sel_hi:[0,1]
	v_pk_mul_f32 v[62:63], v[42:43], v[62:63] op_sel_hi:[0,1]
	v_pk_mul_f32 v[28:29], v[42:43], v[28:29] op_sel_hi:[0,1]
	v_pk_mul_f32 v[64:65], v[42:43], v[64:65] op_sel_hi:[0,1]
	v_pk_mul_f32 v[68:69], v[42:43], v[30:31] op_sel_hi:[0,1]
	v_pk_mul_f32 v[66:67], v[42:43], v[66:67] op_sel_hi:[0,1]
	v_pk_mul_f32 v[70:71], v[42:43], v[32:33] op_sel_hi:[0,1]
	s_waitcnt vmcnt(3)
	v_pk_fma_f32 v[30:31], v[10:11], v[60:61], v[18:19]
	v_pk_fma_f32 v[32:33], v[12:13], v[26:27], v[20:21]
	s_waitcnt vmcnt(2)
	v_pk_fma_f32 v[26:27], v[2:3], v[62:63], v[22:23]
	v_pk_fma_f32 v[28:29], v[4:5], v[28:29], v[24:25]
	s_waitcnt vmcnt(1)
	v_pk_fma_f32 v[22:23], v[6:7], v[64:65], v[50:51]
	v_pk_fma_f32 v[24:25], v[8:9], v[68:69], v[52:53]
	s_waitcnt vmcnt(0)
	v_pk_fma_f32 v[18:19], v[14:15], v[66:67], v[54:55]
	v_pk_fma_f32 v[20:21], v[16:17], v[70:71], v[56:57]
	global_store_dwordx4 v[58:59], v[30:33], off
	global_store_dwordx4 v[58:59], v[26:29], off offset:1024
	global_store_dwordx4 v[58:59], v[22:25], off offset:2048
	global_store_dwordx4 v[58:59], v[18:21], off offset:3072
	s_cbranch_vccnz .LBB0_1210
; __device__ __forceinline__ void rowpass_resid(const Params& p, const float* __restrict__ ga, const float* __restrict__ gb, bool write_xn, bool from_x = false) {
;     ...
;         if (write_xn) {
;             s2 = wave_sum(s2);
;             float r2 = rsqrtf(s2 * (1.0f / DM) + EPS);
; #pragma unroll
;             for (int i = 0; i < 4; ++i) {
;                 float4 g4 = *(const float4*)(gb + lane * 4 + 256 * i);
;                 uint2 o; o.x = pack2(hv[4 * i] * r2 * g4.x, hv[4 * i + 1] * r2 * g4.y);
;                 o.y = pack2(hv[4 * i + 2] * r2 * g4.z, hv[4 * i + 3] * r2 * g4.w);
;                 *(uint2*)(xp + lane * 4 + 256 * i) = o;
;             }
;         }
	v_pk_mul_f32 v[50:51], v[30:31], v[30:31]
	v_pk_mul_f32 v[52:53], v[32:33], v[32:33]
	v_add_f32_e32 v35, v50, v51
	v_add_f32_e32 v35, v52, v35
	v_add_f32_e32 v35, v53, v35
	v_pk_mul_f32 v[54:55], v[26:27], v[26:27]
	v_pk_mul_f32 v[56:57], v[28:29], v[28:29]
	v_add_f32_e32 v35, v54, v35
	v_add_f32_e32 v35, v55, v35
	v_add_f32_e32 v35, v56, v35
	v_pk_mul_f32 v[58:59], v[22:23], v[22:23]
	v_add_f32_e32 v35, v57, v35
	v_add_f32_e32 v35, v58, v35
	v_pk_mul_f32 v[60:61], v[24:25], v[24:25]
	v_add_f32_e32 v35, v59, v35
	v_add_f32_e32 v35, v60, v35
	v_pk_mul_f32 v[62:63], v[18:19], v[18:19]
	v_add_f32_e32 v35, v61, v35
	v_add_f32_e32 v35, v62, v35
	v_pk_mul_f32 v[64:65], v[20:21], v[20:21]
	v_add_f32_e32 v35, v63, v35
	v_add_f32_e32 v35, v64, v35
	v_add_f32_e32 v35, v65, v35
	ds_bpermute_b32 v42, v44, v35
	s_mov_b32 s0, 0x800000
	s_waitcnt lgkmcnt(0)
	v_add_f32_e32 v35, v35, v42
	ds_bpermute_b32 v42, v45, v35
	s_waitcnt lgkmcnt(0)
	v_add_f32_e32 v35, v35, v42
	ds_bpermute_b32 v42, v46, v35
	s_waitcnt lgkmcnt(0)
	v_add_f32_e32 v35, v35, v42
	ds_bpermute_b32 v42, v47, v35
	s_waitcnt lgkmcnt(0)
	v_add_f32_e32 v35, v35, v42
	ds_bpermute_b32 v42, v48, v35
	s_waitcnt lgkmcnt(0)
	v_add_f32_e32 v35, v35, v42
	ds_bpermute_b32 v42, v49, v35
	s_waitcnt lgkmcnt(0)
	v_add_f32_e32 v35, v35, v42
	v_fmamk_f32 v35, v35, 0x3a800000, v174
	v_cmp_gt_f32_e32 vcc, s0, v35
	v_mul_f32_e32 v42, 0x4b800000, v35
	s_nop 0
	v_cndmask_b32_e32 v35, v35, v42, vcc
	v_rsq_f32_e32 v35, v35
	s_nop 0
	v_mul_f32_e32 v42, 0x45800000, v35
	v_cndmask_b32_e32 v42, v35, v42, vcc
	v_pk_mul_f32 v[30:31], v[30:31], v[42:43] op_sel_hi:[1,0]
	v_pk_mul_f32 v[32:33], v[32:33], v[42:43] op_sel_hi:[1,0]
	v_pk_mul_f32 v[26:27], v[26:27], v[42:43] op_sel_hi:[1,0]
	v_pk_mul_f32 v[28:29], v[28:29], v[42:43] op_sel_hi:[1,0]
	v_pk_mul_f32 v[22:23], v[22:23], v[42:43] op_sel_hi:[1,0]
	v_pk_mul_f32 v[24:25], v[24:25], v[42:43] op_sel_hi:[1,0]
	v_pk_mul_f32 v[18:19], v[18:19], v[42:43] op_sel_hi:[1,0]
	v_pk_mul_f32 v[20:21], v[20:21], v[42:43] op_sel_hi:[1,0]
	v_pk_mul_f32 v[30:31], v[84:85], v[30:31]
	v_pk_mul_f32 v[32:33], v[86:87], v[32:33]
	v_cvt_pk_bf16_f32 v30, v30, v31
	v_cvt_pk_bf16_f32 v31, v32, v33
	global_store_dwordx2 v[40:41], v[30:31], off
	v_pk_mul_f32 v[26:27], v[88:89], v[26:27]
	v_pk_mul_f32 v[28:29], v[90:91], v[28:29]
	v_cvt_pk_bf16_f32 v26, v26, v27
	v_cvt_pk_bf16_f32 v27, v28, v29
	global_store_dwordx2 v[40:41], v[26:27], off offset:512
	v_pk_mul_f32 v[22:23], v[22:23], v[92:93]
	v_pk_mul_f32 v[24:25], v[24:25], v[94:95]
	v_cvt_pk_bf16_f32 v22, v22, v23
	v_cvt_pk_bf16_f32 v23, v24, v25
	global_store_dwordx2 v[40:41], v[22:23], off offset:1024
	v_pk_mul_f32 v[18:19], v[18:19], v[96:97]
	v_pk_mul_f32 v[20:21], v[20:21], v[98:99]
	v_cvt_pk_bf16_f32 v18, v18, v19
	v_cvt_pk_bf16_f32 v19, v20, v21
	global_store_dwordx2 v[40:41], v[18:19], off offset:1536
	s_branch .LBB0_1210
